# GEMM phase prologues: second batch of first-unit tile loads issued together with the first (vmcnt 2 -> 8)
# speedup vs baseline: 1.0173x; 1.0085x over previous
; #define PG8_WAIT_V(n) asm volatile("s_waitcnt vmcnt(" #n ")" ::: "memory")
; #define PG8_BAR __builtin_amdgcn_s_barrier()
; template <class Epi, class Sched, bool ALIGN_EPI = false, bool SP2 = false>
; __device__ __forceinline__ void gemm_phase(PG8_LAS unsigned char* lds, const Gemm g, const Sched& S, const Epi& E) {
;     ...
;     for (int i = 0; i < 2; ++i) { int R, C; stage_rc(tid * 16 + i * 8192, R, C); const int Rb = Epi::PERM ? ((R & ~31) + perm32(R & 31)) : R;
;         voffA[i] = (unsigned)(R * K + C) * 2u; voffB[i] = (unsigned)(Rb * K + C) * 2u; }
;     const size_t kstep = (size_t)(BK * 2);
;     const size_t hstep = (size_t)HALF * K * 2;
;     const size_t tstep = 2 * hstep;
;     const unsigned ldsw = (unsigned)wid * 1024u;
;     const int aoff = lds_byte(wr * 64 + fr, fq * 8), boff = lds_byte(wc * 32 + fr, fq * 8);
;     ...
;     Unit cur, nxt; int ui = 0;
;     if (!S.next(0, cur)) return;
;     f32x4 acc[2][2][4][2];
; #pragma unroll
;     for (int a = 0; a < 2; ++a)
; #pragma unroll
;         for (int b = 0; b < 2; ++b)
; #pragma unroll
;             for (int m = 0; m < 4; ++m)
; #pragma unroll
;                 for (int n = 0; n < 2; ++n) acc[a][b][m][n] = (f32x4){0.f, 0.f, 0.f, 0.f};
;     bf16x8 At[4][2], B0[2][2], B1[2][2];
;     const char* cA = (const char*)g.A + (size_t)cur.pm * tstep; const char* cB = (const char*)g.Bt + (size_t)cur.pn * tstep;
;     S.a_ready(cur);
;     if constexpr (SP2) {
;         PG8_STAGE(PG8_SB(0, 0), cB, voffB); PG8_STAGE(PG8_SB(0, 1), cB + hstep, voffB); PG8_STAGE(PG8_SA(0, 0), cA, voffA); PG8_STAGE(PG8_SA(0, 1), cA + hstep, voffA);
;         if (wr == 1) PG8_BAR;
;         PG8_WAIT_V(2); PG8_BAR;
;         PG8_STAGE(PG8_SB(1, 0), cB + kstep, voffB); PG8_STAGE(PG8_SA(1, 0), cA + kstep, voffA); PG8_STAGE(PG8_SB(1, 1), cB + hstep + kstep, voffB);
;         PG8_WAIT_V(6); PG8_BAR;
;     } else {
;         PG8_STAGE(PG8_SB(0, 0), cB, voffB); PG8_STAGE(PG8_SA(0, 0), cA, voffA); PG8_STAGE(PG8_SB(0, 1), cB + hstep, voffB); PG8_STAGE(PG8_SA(0, 1), cA + hstep, voffA);
;         if (wr == 1) PG8_BAR;
;         PG8_WAIT_V(4); PG8_BAR;
;         PG8_STAGE(PG8_SB(1, 0), cB + kstep, voffB); PG8_STAGE(PG8_SA(1, 0), cA + kstep, voffA); PG8_STAGE(PG8_SB(1, 1), cB + hstep + kstep, voffB);
;         PG8_WAIT_V(6); PG8_BAR;
.LBB0_374:
	s_add_u32 s60, s50, 0x12000000
	s_addc_u32 s61, s51, 0
	s_add_u32 s62, s50, 0x1400000
	s_addc_u32 s63, s51, 0
	s_add_u32 s36, s50, 0xa000000
	s_addc_u32 s37, s51, 0
	s_add_u32 s64, s50, 0x10000000
	s_addc_u32 s65, s51, 0
	s_add_u32 s38, s50, 0xe000000
	s_addc_u32 s39, s51, 0
	s_add_u32 s66, s50, 0xc000000
	s_addc_u32 s67, s51, 0
	s_add_u32 s58, s50, 0x8000000
	s_addc_u32 s59, s51, 0
	s_add_u32 s40, s50, 0x6000000
	s_addc_u32 s41, s51, 0
	s_ashr_i32 s92, s24, 31
	s_andn2_b64 vcc, exec, s[0:1]
	s_ashr_i32 s93, s3, 31
	s_cbranch_vccnz .LBB0_446
	v_ashrrev_i32_e32 v1, 31, v8
	v_lshrrev_b32_e32 v1, 26, v1
	v_add_u32_e32 v1, v8, v1
	v_ashrrev_i32_e32 v9, 6, v1
	v_bfe_i32 v1, v8, 27, 1
	v_lshlrev_b32_e32 v0, 4, v8
	v_lshrrev_b32_e32 v1, 22, v1
	v_add_u32_e32 v1, v0, v1
	v_and_b32_e32 v1, 0xfffffc00, v1
	v_sub_u32_e32 v1, v0, v1
	v_lshrrev_b32_e32 v2, 4, v1
	v_bitop3_b32 v1, v2, v1, 32 bitop3:0x6c
	v_ashrrev_i32_e32 v3, 31, v1
	v_lshrrev_b32_e32 v3, 26, v3
	v_add_u32_e32 v3, v1, v3
	v_lshlrev_b32_e32 v2, 3, v9
	v_ashrrev_i32_e32 v10, 6, v3
	v_and_b32_e32 v3, 0xc0, v3
	v_and_b32_e32 v2, -16, v2
	v_sub_u32_e32 v1, v1, v3
	v_mov_b32_e32 v3, 1
	v_add_u32_e32 v2, v10, v2
	v_ashrrev_i16_sdwa v1, v3, sext(v1) dst_sel:DWORD dst_unused:UNUSED_PAD src0_sel:DWORD src1_sel:BYTE_0
	v_lshlrev_b32_e32 v4, 5, v9
	v_bfe_i32 v11, v1, 0, 16
	v_lshlrev_b32_e32 v1, 1, v2
	v_lshrrev_b32_e32 v5, 2, v2
	v_and_b32_e32 v6, 3, v10
	s_mov_b32 s1, 0x1fffe0
	v_and_b32_e32 v4, 32, v4
	v_and_b32_e32 v1, 24, v1
	v_and_b32_e32 v5, 4, v5
	v_and_or_b32 v6, v2, s1, v6
	v_or3_b32 v1, v6, v5, v1
	v_add_lshl_u32 v4, v4, v11, 1
	v_add_u32_e32 v0, 0x2000, v0
	v_lshl_add_u32 v142, v1, 11, v4
	v_ashrrev_i32_e32 v1, 31, v0
	v_lshrrev_b32_e32 v1, 22, v1
	v_add_u32_e32 v1, v0, v1
	v_ashrrev_i32_e32 v12, 10, v1
	v_mul_i32_i24_e32 v1, 0x400, v12
	v_sub_u32_e32 v0, v0, v1
	v_lshrrev_b32_e32 v1, 4, v0
	v_bitop3_b32 v0, v1, v0, 32 bitop3:0x6c
	v_lshl_add_u32 v140, v2, 11, v4
	v_ashrrev_i32_e32 v2, 31, v0
	v_lshrrev_b32_e32 v2, 26, v2
	v_add_u32_e32 v2, v0, v2
	s_ashr_i32 s0, s2, 6
	v_lshlrev_b32_e32 v1, 3, v12
	v_ashrrev_i32_e32 v13, 6, v2
	v_and_b32_e32 v2, 0xc0, v2
	s_ashr_i32 s11, s10, 31
	s_ashr_i32 s7, s6, 31
	v_and_b32_e32 v1, -16, v1
	v_sub_u32_e32 v0, v0, v2
	s_ashr_i32 s4, s2, 8
	s_lshl_b32 s71, s0, 10
	s_lshl_b64 s[12:13], s[10:11], 19
	s_lshl_b64 s[14:15], s[6:7], 19
	v_add_u32_e32 v1, v13, v1
	v_ashrrev_i16_sdwa v0, v3, sext(v0) dst_sel:DWORD dst_unused:UNUSED_PAD src0_sel:DWORD src1_sel:BYTE_0
	s_add_u32 s84, s50, s14
	v_lshlrev_b32_e32 v4, 5, v12
	v_bfe_i32 v14, v0, 0, 16
	v_lshlrev_b32_e32 v0, 1, v1
	v_lshrrev_b32_e32 v2, 2, v1
	v_and_b32_e32 v3, 3, v13
	s_addc_u32 s85, s51, s15
	s_add_i32 s11, s71, 0
	v_and_b32_e32 v4, 32, v4
	v_and_b32_e32 v0, 24, v0
	v_and_b32_e32 v2, 4, v2
	v_and_or_b32 v3, v1, s1, v3
	s_add_i32 m0, s11, 0x10000
	v_or3_b32 v0, v3, v2, v0
	v_add_lshl_u32 v2, v4, v14, 1
	global_load_lds_dwordx4 v142, s[84:85]
	s_add_i32 m0, s11, 0x12000
	v_lshl_add_u32 v146, v0, 11, v2
	s_add_u32 s14, s84, 0x40000
	global_load_lds_dwordx4 v146, s[84:85]
	s_addc_u32 s15, s85, 0
	s_add_i32 m0, s11, 0x14000
	v_lshl_add_u32 v144, v1, 11, v2
	global_load_lds_dwordx4 v142, s[14:15]
	s_add_i32 m0, s11, 0x16000
	s_add_u32 s82, s26, s12
	s_addc_u32 s83, s27, s13
	s_add_i32 s89, s11, 0x2000
	global_load_lds_dwordx4 v146, s[14:15]
	s_mov_b32 m0, s11
	s_add_u32 s12, s82, 0x40000
	global_load_lds_dwordx4 v140, s[82:83]
	s_mov_b32 m0, s89
	s_addc_u32 s13, s83, 0
	s_add_i32 s95, s11, 0x4000
	global_load_lds_dwordx4 v144, s[82:83]
	s_mov_b32 m0, s95
	s_add_i32 s96, s11, 0x6000
	global_load_lds_dwordx4 v140, s[12:13]
	s_mov_b32 m0, s96
	v_mov_b32_e32 v149, 0
	global_load_lds_dwordx4 v144, s[12:13]
	v_mov_b32_e32 v143, v149
	v_mov_b32_e32 v147, v149
	v_mov_b32_e32 v141, v149
	v_mov_b32_e32 v145, v149
	s_cmp_eq_u32 s4, 1
	s_mov_b32 s13, 0
	v_lshl_add_u64 v[4:5], s[84:85], 0, v[142:143]
	v_lshl_add_u64 v[2:3], s[84:85], 0, v[146:147]
	v_lshl_add_u64 v[0:1], s[82:83], 0, v[140:141]
	s_cselect_b64 s[14:15], -1, 0
	v_lshl_add_u64 v[6:7], s[82:83], 0, v[144:145]
	s_add_u32 s16, s50, 0x1100300
	s_addc_u32 s17, s51, 0
	s_add_u32 s18, s50, 0x1100200
	s_addc_u32 s19, s51, 0
	s_add_u32 s20, s50, 0x1100100
	s_mov_b64 s[54:55], 0x80
	s_addc_u32 s21, s51, 0
	s_and_b32 s97, s0, 3
	s_add_i32 m0, s11, 0x18000
	v_lshl_add_u64 v[4:5], v[4:5], 0, s[54:55]
	s_lshl_b32 s5, s4, 13
	s_lshl_b32 s7, s97, 12
	global_load_lds_dwordx4 v[4:5], off
	v_lshl_add_u64 v[2:3], v[2:3], 0, s[54:55]
	s_add_i32 m0, s11, 0x1a000
	s_add_i32 s33, s11, 0x8000
	s_add_i32 s30, s11, 0xa000
	global_load_lds_dwordx4 v[2:3], off
	v_lshl_add_u64 v[0:1], v[0:1], 0, s[54:55]
	s_mov_b32 m0, s33
	s_add_u32 s0, s84, 0x40080
	global_load_lds_dwordx4 v[0:1], off
	v_lshl_add_u64 v[0:1], v[6:7], 0, s[54:55]
	s_mov_b32 m0, s30
	s_addc_u32 s1, s85, 0
	global_load_lds_dwordx4 v[0:1], off
	s_add_i32 m0, s11, 0x1c000
	v_lshl_add_u64 v[0:1], s[0:1], 0, v[142:143]
	global_load_lds_dwordx4 v[0:1], off
	v_lshl_add_u64 v[0:1], s[0:1], 0, v[146:147]
	s_add_i32 m0, s11, 0x1e000
	v_writelane_b32 v255, s16, 1
	global_load_lds_dwordx4 v[0:1], off
	s_cmp_lg_u32 s4, 1
	s_cbranch_scc1 .LBB0_377
	s_barrier
.LBB0_377:
	s_waitcnt vmcnt(8)
	s_barrier
	s_nop 0
	v_writelane_b32 v255, s17, 2
	v_bfe_u32 v2, v8, 4, 2
	v_readlane_b32 s0, v255, 5
	v_and_b32_e32 v1, 15, v8
	v_lshlrev_b32_e32 v0, 4, v2
	v_lshlrev_b32_e32 v148, 6, v2
	v_readlane_b32 s1, v255, 6
	v_lshl_or_b32 v151, s4, 6, v1
	v_lshl_or_b32 v3, v1, 6, v0
	v_lshl_add_u64 v[152:153], s[0:1], 0, v[148:149]
	v_cmp_eq_u32_e64 s[0:1], 0, v1
	v_mov_b32_e32 v1, v149
	v_lshl_add_u64 v[156:157], s[60:61], 0, v[0:1]
	v_lshlrev_b32_e32 v0, 14, v9
	v_and_b32_e32 v0, 0xffff8000, v0
	v_lshl_add_u32 v0, v10, 11, v0
	v_and_b32_e32 v1, 1, v9
	v_lshl_or_b32 v0, v1, 6, v0
	v_lshl_add_u32 v158, v11, 1, v0
	v_lshlrev_b32_e32 v0, 14, v12
	v_lshlrev_b32_e32 v4, 2, v8
	v_and_b32_e32 v0, 0xffff8000, v0
	v_and_b32_e32 v4, 32, v4
	s_waitcnt vmcnt(6)
	s_cmpk_lt_u32 s2, 0x100
	v_lshl_add_u32 v0, v13, 11, v0
	v_and_b32_e32 v1, 1, v12
	v_bitop3_b32 v5, v3, s5, v4 bitop3:0xde
	v_bitop3_b32 v167, v3, s7, v4 bitop3:0xde
	s_cselect_b64 s[56:57], -1, 0
	s_ashr_i32 s5, s4, 31
	v_lshlrev_b32_e32 v148, 5, v2
	v_lshl_or_b32 v0, v1, 6, v0
	s_add_i32 s31, 0, 0x10000
	s_add_i32 s22, 0, 0x14000
	v_lshlrev_b32_e32 v150, 3, v2
	s_lshl_b64 s[72:73], s[4:5], 10
	v_lshl_add_u64 v[154:155], s[62:63], 0, v[148:149]
	v_mov_b32_e32 v159, v149
	v_lshl_add_u32 v160, v14, 1, v0
	v_mov_b32_e32 v161, v149
	v_mov_b64_e32 v[162:163], 0x800
	v_mov_b64_e32 v[164:165], 0x7ff
	v_add_u32_e32 v171, s31, v167
	v_add_u32_e32 v173, s22, v167
	v_add_u32_e32 v175, 0, v5
	v_mov_b32_e32 v177, 0x358637bd
	s_mov_b32 s23, 0x800000
	v_mbcnt_hi_u32_b32 v181, -1, v224
	s_mov_b32 s16, 0
	s_barrier
	s_branch .LBB0_380

; #define PG8_WAIT_V(n) asm volatile("s_waitcnt vmcnt(" #n ")" ::: "memory")
; #define PG8_BAR __builtin_amdgcn_s_barrier()
; template <class Epi, class Sched, bool ALIGN_EPI = false, bool SP2 = false>
; __device__ __forceinline__ void gemm_phase(PG8_LAS unsigned char* lds, const Gemm g, const Sched& S, const Epi& E) {
;     ...
;     for (int i = 0; i < 2; ++i) { int R, C; stage_rc(tid * 16 + i * 8192, R, C); const int Rb = Epi::PERM ? ((R & ~31) + perm32(R & 31)) : R;
;         voffA[i] = (unsigned)(R * K + C) * 2u; voffB[i] = (unsigned)(Rb * K + C) * 2u; }
;     const size_t kstep = (size_t)(BK * 2);
;     const size_t hstep = (size_t)HALF * K * 2;
;     const size_t tstep = 2 * hstep;
;     const unsigned ldsw = (unsigned)wid * 1024u;
;     const int aoff = lds_byte(wr * 64 + fr, fq * 8), boff = lds_byte(wc * 32 + fr, fq * 8);
;     ...
;     Unit cur, nxt; int ui = 0;
;     if (!S.next(0, cur)) return;
;     f32x4 acc[2][2][4][2];
; #pragma unroll
;     for (int a = 0; a < 2; ++a)
; #pragma unroll
;         for (int b = 0; b < 2; ++b)
; #pragma unroll
;             for (int m = 0; m < 4; ++m)
; #pragma unroll
;                 for (int n = 0; n < 2; ++n) acc[a][b][m][n] = (f32x4){0.f, 0.f, 0.f, 0.f};
;     bf16x8 At[4][2], B0[2][2], B1[2][2];
;     const char* cA = (const char*)g.A + (size_t)cur.pm * tstep; const char* cB = (const char*)g.Bt + (size_t)cur.pn * tstep;
;     S.a_ready(cur);
;     if constexpr (SP2) {
;         PG8_STAGE(PG8_SB(0, 0), cB, voffB); PG8_STAGE(PG8_SB(0, 1), cB + hstep, voffB); PG8_STAGE(PG8_SA(0, 0), cA, voffA); PG8_STAGE(PG8_SA(0, 1), cA + hstep, voffA);
;         if (wr == 1) PG8_BAR;
;         PG8_WAIT_V(2); PG8_BAR;
;         PG8_STAGE(PG8_SB(1, 0), cB + kstep, voffB); PG8_STAGE(PG8_SA(1, 0), cA + kstep, voffA); PG8_STAGE(PG8_SB(1, 1), cB + hstep + kstep, voffB);
;         PG8_WAIT_V(6); PG8_BAR;
;     } else {
;         PG8_STAGE(PG8_SB(0, 0), cB, voffB); PG8_STAGE(PG8_SA(0, 0), cA, voffA); PG8_STAGE(PG8_SB(0, 1), cB + hstep, voffB); PG8_STAGE(PG8_SA(0, 1), cA + hstep, voffA);
;         if (wr == 1) PG8_BAR;
;         PG8_WAIT_V(4); PG8_BAR;
;         PG8_STAGE(PG8_SB(1, 0), cB + kstep, voffB); PG8_STAGE(PG8_SA(1, 0), cA + kstep, voffA); PG8_STAGE(PG8_SB(1, 1), cB + hstep + kstep, voffB);
;         PG8_WAIT_V(6); PG8_BAR;
.LBB0_737:
	s_add_u32 s6, s50, 0x1500000
	s_addc_u32 s7, s51, 0
	s_and_b64 vcc, exec, s[44:45]
	s_cbranch_vccnz .LBB0_773
	v_ashrrev_i32_e32 v1, 31, v8
	v_lshrrev_b32_e32 v1, 26, v1
	v_add_u32_e32 v1, v8, v1
	v_ashrrev_i32_e32 v9, 6, v1
	v_bfe_i32 v1, v8, 27, 1
	v_lshlrev_b32_e32 v0, 4, v8
	v_lshrrev_b32_e32 v1, 22, v1
	v_add_u32_e32 v1, v0, v1
	v_and_b32_e32 v1, 0xfffffc00, v1
	v_sub_u32_e32 v1, v0, v1
	v_lshrrev_b32_e32 v2, 4, v1
	v_bitop3_b32 v1, v2, v1, 32 bitop3:0x6c
	v_ashrrev_i32_e32 v3, 31, v1
	v_lshrrev_b32_e32 v3, 26, v3
	v_add_u32_e32 v3, v1, v3
	v_lshlrev_b32_e32 v2, 3, v9
	v_ashrrev_i32_e32 v10, 6, v3
	v_and_b32_e32 v3, 0xc0, v3
	v_and_b32_e32 v2, -16, v2
	v_sub_u32_e32 v1, v1, v3
	v_mov_b32_e32 v3, 1
	v_add_u32_e32 v2, v10, v2
	v_ashrrev_i16_sdwa v1, v3, sext(v1) dst_sel:DWORD dst_unused:UNUSED_PAD src0_sel:DWORD src1_sel:BYTE_0
	v_lshlrev_b32_e32 v4, 5, v9
	v_bfe_i32 v11, v1, 0, 16
	v_lshlrev_b32_e32 v1, 1, v2
	v_lshrrev_b32_e32 v5, 2, v2
	v_and_b32_e32 v6, 3, v10
	s_mov_b32 s2, 0x1fffe0
	v_and_b32_e32 v4, 32, v4
	v_and_b32_e32 v1, 24, v1
	v_and_b32_e32 v5, 4, v5
	v_and_or_b32 v6, v2, s2, v6
	v_or3_b32 v1, v6, v5, v1
	v_add_lshl_u32 v4, v4, v11, 1
	v_add_u32_e32 v0, 0x2000, v0
	v_lshl_add_u32 v130, v1, 11, v4
	v_ashrrev_i32_e32 v1, 31, v0
	v_lshrrev_b32_e32 v1, 22, v1
	v_add_u32_e32 v1, v0, v1
	v_ashrrev_i32_e32 v12, 10, v1
	v_mul_i32_i24_e32 v1, 0x400, v12
	v_sub_u32_e32 v0, v0, v1
	v_lshrrev_b32_e32 v1, 4, v0
	v_bitop3_b32 v0, v1, v0, 32 bitop3:0x6c
	v_lshl_add_u32 v128, v2, 11, v4
	v_ashrrev_i32_e32 v2, 31, v0
	v_lshrrev_b32_e32 v2, 26, v2
	v_add_u32_e32 v2, v0, v2
	v_lshlrev_b32_e32 v1, 3, v12
	v_ashrrev_i32_e32 v13, 6, v2
	v_and_b32_e32 v2, 0xc0, v2
	v_and_b32_e32 v1, -16, v1
	v_sub_u32_e32 v0, v0, v2
	s_ashr_i32 s1, s0, 6
	v_add_u32_e32 v1, v13, v1
	v_ashrrev_i16_sdwa v0, v3, sext(v0) dst_sel:DWORD dst_unused:UNUSED_PAD src0_sel:DWORD src1_sel:BYTE_0
	v_and_b32_e32 v3, 3, v13
	s_ashr_i32 s61, s60, 31
	s_ashr_i32 s9, s8, 31
	v_and_or_b32 v3, v1, s2, v3
	s_ashr_i32 s4, s0, 8
	s_lshl_b32 s2, s1, 10
	s_lshl_b64 s[10:11], s[60:61], 19
	s_lshl_b64 s[12:13], s[8:9], 19
	s_add_u32 s64, s46, s12
	v_lshlrev_b32_e32 v4, 5, v12
	v_bfe_i32 v14, v0, 0, 16
	v_lshlrev_b32_e32 v0, 1, v1
	v_lshrrev_b32_e32 v2, 2, v1
	s_addc_u32 s65, s47, s13
	s_add_i32 s22, s2, 0
	v_and_b32_e32 v4, 32, v4
	v_and_b32_e32 v0, 24, v0
	v_and_b32_e32 v2, 4, v2
	s_add_i32 m0, s22, 0x10000
	v_or3_b32 v0, v3, v2, v0
	v_add_lshl_u32 v2, v4, v14, 1
	global_load_lds_dwordx4 v130, s[64:65]
	s_add_i32 m0, s22, 0x12000
	v_lshl_add_u32 v134, v0, 11, v2
	s_add_u32 s12, s64, 0x40000
	global_load_lds_dwordx4 v134, s[64:65]
	s_addc_u32 s13, s65, 0
	s_add_i32 m0, s22, 0x14000
	v_lshl_add_u32 v132, v1, 11, v2
	global_load_lds_dwordx4 v130, s[12:13]
	s_add_i32 m0, s22, 0x16000
	s_add_u32 s62, s26, s10
	s_addc_u32 s63, s27, s11
	s_add_i32 s23, s22, 0x2000
	global_load_lds_dwordx4 v134, s[12:13]
	s_mov_b32 m0, s22
	s_add_u32 s10, s62, 0x40000
	global_load_lds_dwordx4 v128, s[62:63]
	s_mov_b32 m0, s23
	s_addc_u32 s11, s63, 0
	s_add_i32 s30, s22, 0x4000
	global_load_lds_dwordx4 v132, s[62:63]
	s_mov_b32 m0, s30
	s_add_i32 s31, s22, 0x6000
	global_load_lds_dwordx4 v128, s[10:11]
	s_mov_b32 m0, s31
	v_mov_b32_e32 v131, 0
	global_load_lds_dwordx4 v132, s[10:11]
	v_mov_b32_e32 v135, v131
	v_mov_b32_e32 v129, v131
	v_mov_b32_e32 v133, v131
	s_cmp_eq_u32 s4, 1
	s_mov_b32 s9, 0
	v_lshl_add_u64 v[6:7], s[64:65], 0, v[130:131]
	v_lshl_add_u64 v[4:5], s[64:65], 0, v[134:135]
	v_lshl_add_u64 v[0:1], s[62:63], 0, v[128:129]
	s_cselect_b64 s[10:11], -1, 0
	v_lshl_add_u64 v[2:3], s[62:63], 0, v[132:133]
	s_mov_b64 s[12:13], 0x80
	s_and_b32 s33, s1, 3
	s_add_i32 m0, s22, 0x18000
	v_lshl_add_u64 v[6:7], v[6:7], 0, s[12:13]
	s_lshl_b32 s1, s4, 13
	s_lshl_b32 s5, s33, 12
	global_load_lds_dwordx4 v[6:7], off
	v_lshl_add_u64 v[4:5], v[4:5], 0, s[12:13]
	s_add_i32 m0, s22, 0x1a000
	s_add_i32 s44, s22, 0x8000
	s_add_i32 s45, s22, 0xa000
	global_load_lds_dwordx4 v[4:5], off
	v_lshl_add_u64 v[0:1], v[0:1], 0, s[12:13]
	s_mov_b32 m0, s44
	s_add_u32 s14, s64, 0x40080
	global_load_lds_dwordx4 v[0:1], off
	v_lshl_add_u64 v[0:1], v[2:3], 0, s[12:13]
	s_mov_b32 m0, s45
	s_addc_u32 s15, s65, 0
	global_load_lds_dwordx4 v[0:1], off
	s_add_i32 m0, s22, 0x1c000
	v_lshl_add_u64 v[0:1], s[14:15], 0, v[130:131]
	global_load_lds_dwordx4 v[0:1], off
	v_lshl_add_u64 v[0:1], s[14:15], 0, v[134:135]
	s_add_i32 m0, s22, 0x1e000
	s_cmpk_lt_u32 s0, 0x100
	global_load_lds_dwordx4 v[0:1], off
	s_cmp_lg_u32 s4, 1
	s_cbranch_scc1 .LBB0_740
	s_barrier
.LBB0_740:
	s_waitcnt vmcnt(8)
	s_barrier
	v_bfe_u32 v1, v8, 4, 2
	v_and_b32_e32 v0, 15, v8
	v_lshlrev_b32_e32 v3, 4, v1
	v_lshl_or_b32 v148, s4, 6, v0
	v_lshl_or_b32 v0, v0, 6, v3
	v_lshlrev_b32_e32 v3, 2, v8
	v_and_b32_e32 v3, 32, v3
	v_bitop3_b32 v4, v0, s1, v3 bitop3:0xde
	v_bitop3_b32 v149, v0, s5, v3 bitop3:0xde
	v_lshlrev_b32_e32 v0, 14, v9
	v_and_b32_e32 v0, 0xffff8000, v0
	v_lshlrev_b32_e32 v2, 3, v1
	v_cmp_eq_u32_e64 s[0:1], 0, v1
	v_lshl_add_u32 v0, v10, 11, v0
	v_and_b32_e32 v1, 1, v9
	v_lshl_or_b32 v0, v1, 6, v0
	v_lshl_add_u32 v136, v11, 1, v0
	v_lshlrev_b32_e32 v0, 14, v12
	v_and_b32_e32 v0, 0xffff8000, v0
	s_waitcnt vmcnt(6)
	v_lshl_add_u32 v0, v13, 11, v0
	v_and_b32_e32 v1, 1, v12
	s_cselect_b64 s[14:15], -1, 0
	v_lshl_or_b32 v0, v1, 6, v0
	s_add_i32 s68, 0, 0x10000
	s_add_i32 s69, 0, 0x14000
	v_lshl_or_b32 v150, s33, 5, v2
	v_mov_b32_e32 v137, v131
	v_lshl_add_u32 v138, v14, 1, v0
	v_mov_b32_e32 v139, v131
	v_mov_b64_e32 v[140:141], 0x200
	v_mov_b64_e32 v[142:143], 0x1ff
	v_add_u32_e32 v151, s68, v149
	v_add_u32_e32 v152, s69, v149
	v_add_u32_e32 v153, 0, v4
	v_mbcnt_hi_u32_b32 v154, -1, v224
	s_mov_b32 s70, 0
	s_barrier
	s_branch .LBB0_743

; #define PG8_WAIT_V(n) asm volatile("s_waitcnt vmcnt(" #n ")" ::: "memory")
; #define PG8_BAR __builtin_amdgcn_s_barrier()
; template <class Epi, class Sched, bool ALIGN_EPI = false, bool SP2 = false>
; __device__ __forceinline__ void gemm_phase(PG8_LAS unsigned char* lds, const Gemm g, const Sched& S, const Epi& E) {
;     ...
;     for (int i = 0; i < 2; ++i) { int R, C; stage_rc(tid * 16 + i * 8192, R, C); const int Rb = Epi::PERM ? ((R & ~31) + perm32(R & 31)) : R;
;         voffA[i] = (unsigned)(R * K + C) * 2u; voffB[i] = (unsigned)(Rb * K + C) * 2u; }
;     const size_t kstep = (size_t)(BK * 2);
;     const size_t hstep = (size_t)HALF * K * 2;
;     const size_t tstep = 2 * hstep;
;     const unsigned ldsw = (unsigned)wid * 1024u;
;     const int aoff = lds_byte(wr * 64 + fr, fq * 8), boff = lds_byte(wc * 32 + fr, fq * 8);
;     ...
;     Unit cur, nxt; int ui = 0;
;     if (!S.next(0, cur)) return;
;     f32x4 acc[2][2][4][2];
; #pragma unroll
;     for (int a = 0; a < 2; ++a)
; #pragma unroll
;         for (int b = 0; b < 2; ++b)
; #pragma unroll
;             for (int m = 0; m < 4; ++m)
; #pragma unroll
;                 for (int n = 0; n < 2; ++n) acc[a][b][m][n] = (f32x4){0.f, 0.f, 0.f, 0.f};
;     bf16x8 At[4][2], B0[2][2], B1[2][2];
;     const char* cA = (const char*)g.A + (size_t)cur.pm * tstep; const char* cB = (const char*)g.Bt + (size_t)cur.pn * tstep;
;     S.a_ready(cur);
;     if constexpr (SP2) {
;         PG8_STAGE(PG8_SB(0, 0), cB, voffB); PG8_STAGE(PG8_SB(0, 1), cB + hstep, voffB); PG8_STAGE(PG8_SA(0, 0), cA, voffA); PG8_STAGE(PG8_SA(0, 1), cA + hstep, voffA);
;         if (wr == 1) PG8_BAR;
;         PG8_WAIT_V(2); PG8_BAR;
;         PG8_STAGE(PG8_SB(1, 0), cB + kstep, voffB); PG8_STAGE(PG8_SA(1, 0), cA + kstep, voffA); PG8_STAGE(PG8_SB(1, 1), cB + hstep + kstep, voffB);
;         PG8_WAIT_V(6); PG8_BAR;
;     } else {
;         PG8_STAGE(PG8_SB(0, 0), cB, voffB); PG8_STAGE(PG8_SA(0, 0), cA, voffA); PG8_STAGE(PG8_SB(0, 1), cB + hstep, voffB); PG8_STAGE(PG8_SA(0, 1), cA + hstep, voffA);
;         if (wr == 1) PG8_BAR;
;         PG8_WAIT_V(4); PG8_BAR;
;         PG8_STAGE(PG8_SB(1, 0), cB + kstep, voffB); PG8_STAGE(PG8_SA(1, 0), cA + kstep, voffA); PG8_STAGE(PG8_SB(1, 1), cB + hstep + kstep, voffB);
;         PG8_WAIT_V(6); PG8_BAR;
.Lb3_p4_top:
	s_add_u32 s10, s50, 0xf000000
	s_addc_u32 s11, s51, 0
	v_mov_b32_e32 v11, v234
	s_waitcnt lgkmcnt(0)
	s_barrier
	s_cmpk_lt_i32 s3, 0x480
	s_nop 0
	v_readfirstlane_b32 s1, v11
	s_cbranch_scc0 .LBB0_855
	v_lshlrev_b32_e32 v0, 4, v11
	v_add_u32_e32 v1, 0x2000, v0
	v_ashrrev_i32_e32 v2, 31, v1
	v_lshrrev_b32_e32 v2, 22, v2
	v_add_u32_e32 v2, v1, v2
	v_ashrrev_i32_e32 v8, 10, v2
	v_mul_i32_i24_e32 v2, 0x400, v8
	v_sub_u32_e32 v1, v1, v2
	v_lshrrev_b32_e32 v2, 4, v1
	v_bitop3_b32 v1, v2, v1, 32 bitop3:0x6c
	v_ashrrev_i32_e32 v2, 31, v1
	v_lshrrev_b32_e32 v2, 26, v2
	v_add_u32_e32 v2, v1, v2
	v_lshlrev_b32_e32 v3, 3, v8
	v_ashrrev_i32_e32 v9, 6, v2
	v_and_b32_e32 v3, -16, v3
	v_add_u32_e32 v3, v9, v3
	v_and_b32_e32 v4, 3, v9
	s_mov_b32 s0, 0x1fffe0
	v_lshrrev_b32_e32 v5, 2, v3
	v_lshlrev_b32_e32 v6, 1, v3
	v_and_b32_e32 v2, 0xc0, v2
	v_and_or_b32 v4, v3, s0, v4
	v_and_b32_e32 v5, 4, v5
	v_and_b32_e32 v6, 24, v6
	v_sub_u32_e32 v1, v1, v2
	v_mov_b32_e32 v2, 1
	v_or3_b32 v4, v4, v5, v6
	v_lshlrev_b32_e32 v5, 5, v8
	v_ashrrev_i16_sdwa v1, v2, sext(v1) dst_sel:DWORD dst_unused:UNUSED_PAD src0_sel:DWORD src1_sel:BYTE_0
	v_and_b32_e32 v5, 32, v5
	v_bfe_i32 v10, v1, 0, 16
	v_add_lshl_u32 v1, v5, v10, 1
	v_lshl_add_u32 v132, v4, 11, v1
	v_lshl_add_u32 v134, v3, 11, v1
	v_bfe_i32 v1, v11, 27, 1
	v_lshrrev_b32_e32 v1, 22, v1
	v_add_u32_e32 v1, v0, v1
	v_and_b32_e32 v1, 0xfffffc00, v1
	v_sub_u32_e32 v0, v0, v1
	v_lshrrev_b32_e32 v1, 4, v0
	v_ashrrev_i32_e32 v3, 31, v11
	v_bitop3_b32 v0, v1, v0, 32 bitop3:0x6c
	v_lshrrev_b32_e32 v3, 26, v3
	v_ashrrev_i32_e32 v1, 31, v0
	v_add_u32_e32 v3, v11, v3
	v_lshrrev_b32_e32 v1, 26, v1
	v_ashrrev_i32_e32 v13, 6, v3
	v_add_u32_e32 v1, v0, v1
	v_lshlrev_b32_e32 v3, 3, v13
	v_ashrrev_i32_e32 v12, 6, v1
	v_and_b32_e32 v3, -16, v3
	v_add_u32_e32 v3, v12, v3
	v_and_b32_e32 v4, 3, v12
	v_and_or_b32 v4, v3, s0, v4
	s_lshr_b32 s0, s93, 29
	s_add_i32 s0, s3, s0
	s_ashr_i32 s2, s1, 6
	s_ashr_i32 s4, s0, 3
	s_and_b32 s0, s0, -8
	s_ashr_i32 s12, s1, 8
	s_lshl_b32 s22, s2, 10
	s_sub_i32 s0, s3, s0
	s_cmp_lt_i32 s0, 0
	s_movk_i32 s23, 0x91
	s_cselect_b32 s5, s23, 0x90
	s_mul_i32 s0, s0, s5
	s_add_i32 s0, s0, s4
	s_mul_hi_i32 s4, s0, 0x38e38e39
	s_lshr_b32 s5, s4, 31
	s_ashr_i32 s4, s4, 4
	s_add_i32 s4, s4, s5
	s_lshl_b32 s5, s4, 3
	s_mulk_i32 s4, 0x48
	s_sub_i32 s4, s0, s4
	s_bfe_i32 s0, s4, 0x80000
	s_bfe_u32 s0, s0, 0x3000c
	s_add_i32 s8, s4, s0
	s_bfe_i32 s0, s8, 0x80000
	s_and_b32 s8, s8, 0xf8
	s_sub_i32 s4, s4, s8
	s_sext_i32_i16 s0, s0
	s_sext_i32_i8 s4, s4
	v_lshrrev_b32_e32 v5, 2, v3
	v_lshlrev_b32_e32 v6, 1, v3
	v_and_b32_e32 v1, 0xc0, v1
	s_lshr_b32 s0, s0, 3
	s_add_i32 s4, s5, s4
	v_and_b32_e32 v5, 4, v5
	v_and_b32_e32 v6, 24, v6
	v_sub_u32_e32 v0, v0, v1
	s_ashr_i32 s5, s4, 31
	s_bfe_i64 s[8:9], s[0:1], 0x100000
	v_or3_b32 v4, v4, v5, v6
	v_lshlrev_b32_e32 v5, 5, v13
	v_ashrrev_i16_sdwa v0, v2, sext(v0) dst_sel:DWORD dst_unused:UNUSED_PAD src0_sel:DWORD src1_sel:BYTE_0
	s_lshl_b64 s[14:15], s[4:5], 19
	s_lshl_b64 s[8:9], s[8:9], 19
	v_and_b32_e32 v5, 32, v5
	v_bfe_i32 v14, v0, 0, 16
	s_add_u32 s8, s42, s8
	v_add_lshl_u32 v0, v5, v14, 1
	s_addc_u32 s9, s43, s9
	s_add_i32 s30, s22, 0
	v_lshl_add_u32 v136, v4, 11, v0
	s_add_i32 m0, s30, 0x10000
	v_lshl_add_u32 v138, v3, 11, v0
	global_load_lds_dwordx4 v136, s[8:9]
	s_add_i32 m0, s30, 0x12000
	s_add_u32 s16, s8, 0x40000
	global_load_lds_dwordx4 v132, s[8:9]
	s_addc_u32 s17, s9, 0
	s_add_i32 m0, s30, 0x14000
	v_mov_b32_e32 v141, 0
	global_load_lds_dwordx4 v136, s[16:17]
	s_add_i32 m0, s30, 0x16000
	s_add_u32 s78, s40, s14
	s_addc_u32 s79, s41, s15
	s_add_i32 s31, s30, 0x2000
	global_load_lds_dwordx4 v132, s[16:17]
	s_mov_b32 m0, s30
	s_add_u32 s14, s78, 0x40000
	global_load_lds_dwordx4 v138, s[78:79]
	s_mov_b32 m0, s31
	s_addc_u32 s15, s79, 0
	s_add_i32 s33, s30, 0x4000
	global_load_lds_dwordx4 v134, s[78:79]
	s_mov_b32 m0, s33
	s_add_i32 s53, s30, 0x6000
	global_load_lds_dwordx4 v138, s[14:15]
	s_mov_b32 m0, s53
	v_mov_b32_e32 v137, v141
	global_load_lds_dwordx4 v134, s[14:15]
	v_mov_b32_e32 v133, v141
	v_mov_b32_e32 v139, v141
	v_mov_b32_e32 v135, v141
	s_cmp_eq_u32 s12, 1
	s_mov_b32 s13, 0
	v_lshl_add_u64 v[6:7], s[8:9], 0, v[136:137]
	v_lshl_add_u64 v[2:3], s[8:9], 0, v[132:133]
	v_lshl_add_u64 v[0:1], s[78:79], 0, v[138:139]
	s_cselect_b64 s[14:15], -1, 0
	v_lshl_add_u64 v[4:5], s[78:79], 0, v[134:135]
	s_add_u32 s5, s50, 0x1100500
	s_addc_u32 s44, s51, 0
	s_add_u32 s16, s50, 0x1100400
	s_mov_b64 s[18:19], 0x80
	s_addc_u32 s17, s51, 0
	s_and_b32 s59, s2, 3
	s_add_i32 m0, s30, 0x18000
	v_lshl_add_u64 v[6:7], v[6:7], 0, s[18:19]
	s_lshl_b32 s45, s12, 13
	s_lshl_b32 s46, s59, 12
	global_load_lds_dwordx4 v[6:7], off
	v_lshl_add_u64 v[2:3], v[2:3], 0, s[18:19]
	s_add_i32 m0, s30, 0x1a000
	s_add_i32 s61, s30, 0x8000
	s_add_i32 s69, s30, 0xa000
	global_load_lds_dwordx4 v[2:3], off
	v_lshl_add_u64 v[0:1], v[0:1], 0, s[18:19]
	s_mov_b32 m0, s61
	s_add_u32 s20, s8, 0x40080
	global_load_lds_dwordx4 v[0:1], off
	v_lshl_add_u64 v[0:1], v[4:5], 0, s[18:19]
	s_mov_b32 m0, s69
	s_addc_u32 s21, s9, 0
	global_load_lds_dwordx4 v[0:1], off
	s_add_i32 m0, s30, 0x1c000
	v_lshl_add_u64 v[0:1], s[20:21], 0, v[136:137]
	global_load_lds_dwordx4 v[0:1], off
	v_lshl_add_u64 v[0:1], s[20:21], 0, v[132:133]
	s_add_i32 m0, s30, 0x1e000
	s_or_b32 s86, s59, 0xffffffec
	global_load_lds_dwordx4 v[0:1], off
	s_cmp_lg_u32 s12, 1
	s_cbranch_scc1 .LBB0_829
	s_barrier
; #define PG8_STAGE(bufoff, gbase, voff) do { _Pragma("unroll") for (int _i = 0; _i < 2; ++_i) \
;         __builtin_amdgcn_global_load_lds((const unsigned*)((const char*)(gbase) + (voff)[_i]), (PG8_LAS unsigned*)(lds + (bufoff) + ldsw + _i * 8192), 16, 0, 0); } while (0)
; #define PG8_WAIT_V(n) asm volatile("s_waitcnt vmcnt(" #n ")" ::: "memory")
; #define PG8_BAR __builtin_amdgcn_s_barrier()
; template <class Epi, class Sched, bool ALIGN_EPI = false, bool SP2 = false>
; __device__ __forceinline__ void gemm_phase(PG8_LAS unsigned char* lds, const Gemm g, const Sched& S, const Epi& E) {
;     ...
;         if (wr == 1) PG8_BAR;
;         PG8_WAIT_V(4); PG8_BAR;
;         PG8_STAGE(PG8_SB(1, 0), cB + kstep, voffB); PG8_STAGE(PG8_SA(1, 0), cA + kstep, voffA); PG8_STAGE(PG8_SB(1, 1), cB + hstep + kstep, voffB);
;         PG8_WAIT_V(6); PG8_BAR;
;     }
;     for (;;) {
;         const bool has_next = S.next(ui + 1, nxt);
;         const char* nA = has_next ? (const char*)g.A + (size_t)nxt.pm * tstep : cA; const char* nB = has_next ? (const char*)g.Bt + (size_t)nxt.pn * tstep : cB;
;     __device__ __forceinline__ void operator()(const f32x4 (&acc)[2][2][4][2], const Unit& u, int wr, int wc, int fr, int fq) const {
;     ...
;             if (u.pn < 4) { mode = 0; dst = (bf16_t*)(ws + WS_QC); gain = gains + 256; head = u.pn * 4 + wc; hpb = 16; qsc = SC_LOG2; }
;             else if (u.pn == 4) { hpb = 2; if (wc < 2) { mode = 0; dst = (bf16_t*)(ws + WS_KC); gain = gains + 320; head = wc; } else { mode = 1; dst = (bf16_t*)(ws + WS_VTC); head = wc - 2; } }
.LBB0_829:
	s_waitcnt vmcnt(8)
	s_barrier
	v_bfe_u32 v1, v11, 4, 2
	v_and_b32_e32 v0, 15, v11
	v_lshlrev_b32_e32 v140, 4, v1
	v_lshlrev_b32_e32 v2, 2, v11
	s_cmpk_lt_u32 s1, 0x100
	v_lshl_or_b32 v143, s12, 6, v0
	v_lshl_or_b32 v0, v0, 6, v140
	v_and_b32_e32 v2, 32, v2
	s_cselect_b64 s[20:21], -1, 0
	s_cmp_gt_u32 s59, 1
	v_lshl_add_u64 v[144:145], s[6:7], 0, v[140:141]
	v_readlane_b32 s6, v255, 5
	s_sext_i32_i8 s2, s0
	v_lshlrev_b32_e32 v142, 3, v1
	v_bitop3_b32 v3, v0, s45, v2 bitop3:0xde
	v_bitop3_b32 v225, v0, s46, v2 bitop3:0xde
	s_cselect_b64 s[0:1], -1, 0
	v_lshlrev_b32_e32 v0, 6, v1
	v_mov_b32_e32 v1, v141
	v_readlane_b32 s7, v255, 6
	s_add_i32 s12, s59, -2
	s_waitcnt vmcnt(6)
	v_lshl_add_u64 v[148:149], s[10:11], 0, v[140:141]
	v_lshl_add_u64 v[146:147], s[6:7], 0, v[0:1]
	v_cndmask_b32_e64 v0, 0, 1, s[0:1]
	v_and_b32_e32 v1, 1, v13
	v_readfirstlane_b32 s88, v0
	v_lshlrev_b32_e32 v0, 14, v13
	v_and_b32_e32 v0, 0xffff8000, v0
	v_lshl_add_u32 v0, v12, 11, v0
	s_and_b64 s[0:1], s[0:1], exec
	v_lshl_or_b32 v0, v1, 6, v0
	s_mov_b32 s0, 0xe800000
	v_lshl_add_u32 v150, v14, 1, v0
	v_lshlrev_b32_e32 v0, 14, v8
	s_cselect_b32 s0, s0, 0xe000000
	v_and_b32_e32 v0, 0xffff8000, v0
	s_cselect_b32 s45, s35, s44
	s_cselect_b32 s44, s34, s5
	s_add_u32 s46, s50, s0
	v_lshl_add_u32 v0, v9, 11, v0
	v_and_b32_e32 v1, 1, v8
	s_addc_u32 s47, s51, 0
	v_lshl_or_b32 v0, v1, 6, v0
	s_add_i32 s89, 0, 0x10000
	s_add_i32 s90, 0, 0x14000
	s_min_u32 s87, s12, s59
	v_mov_b32_e32 v151, v141
	v_lshl_add_u32 v152, v10, 1, v0
	v_mov_b32_e32 v153, v141
	s_movk_i32 vcc_lo, 0x480
	s_movk_i32 vcc_hi, 0x47f
	s_cmp_eq_u32 s100, 0
	s_cselect_b32 vcc_lo, 0x400, vcc_lo
	s_cselect_b32 vcc_hi, 0x3ff, vcc_hi
	v_mov_b32_e32 v154, vcc_lo
	v_mov_b32_e32 v155, 0
	v_mov_b32_e32 v156, vcc_hi
	v_mov_b32_e32 v157, 0
	v_add_u32_e32 v226, s89, v225
	v_add_u32_e32 v227, s90, v225
	v_add_u32_e32 v228, 0, v3
	v_mbcnt_hi_u32_b32 v229, -1, v224
	s_mov_b32 s52, 0x3a800000
	s_mov_b32 s58, 0x358637bd
	s_mov_b32 s91, 0x800000
	s_mov_b32 s60, 0x45800000
	s_mov_b64 s[62:63], 0x4800
	s_mov_b64 s[64:65], 0x5000
	s_movk_i32 s94, 0x5000
	s_mov_b64 s[66:67], 0x5800
	s_mov_b32 s68, 0x3c800000
	s_mov_b32 s95, 0
	s_barrier
	s_branch .LBB0_832

; #define PG8_WAIT_V(n) asm volatile("s_waitcnt vmcnt(" #n ")" ::: "memory")
; #define PG8_BAR __builtin_amdgcn_s_barrier()
; template <class Epi, class Sched, bool ALIGN_EPI = false, bool SP2 = false>
; __device__ __forceinline__ void gemm_phase(PG8_LAS unsigned char* lds, const Gemm g, const Sched& S, const Epi& E) {
;     ...
;     for (int i = 0; i < 2; ++i) { int R, C; stage_rc(tid * 16 + i * 8192, R, C); const int Rb = Epi::PERM ? ((R & ~31) + perm32(R & 31)) : R;
;         voffA[i] = (unsigned)(R * K + C) * 2u; voffB[i] = (unsigned)(Rb * K + C) * 2u; }
;     const size_t kstep = (size_t)(BK * 2);
;     const size_t hstep = (size_t)HALF * K * 2;
;     const size_t tstep = 2 * hstep;
;     const unsigned ldsw = (unsigned)wid * 1024u;
;     const int aoff = lds_byte(wr * 64 + fr, fq * 8), boff = lds_byte(wc * 32 + fr, fq * 8);
;     ...
;     Unit cur, nxt; int ui = 0;
;     if (!S.next(0, cur)) return;
;     f32x4 acc[2][2][4][2];
; #pragma unroll
;     for (int a = 0; a < 2; ++a)
; #pragma unroll
;         for (int b = 0; b < 2; ++b)
; #pragma unroll
;             for (int m = 0; m < 4; ++m)
; #pragma unroll
;                 for (int n = 0; n < 2; ++n) acc[a][b][m][n] = (f32x4){0.f, 0.f, 0.f, 0.f};
;     bf16x8 At[4][2], B0[2][2], B1[2][2];
;     const char* cA = (const char*)g.A + (size_t)cur.pm * tstep; const char* cB = (const char*)g.Bt + (size_t)cur.pn * tstep;
;     S.a_ready(cur);
;     if constexpr (SP2) {
;         PG8_STAGE(PG8_SB(0, 0), cB, voffB); PG8_STAGE(PG8_SB(0, 1), cB + hstep, voffB); PG8_STAGE(PG8_SA(0, 0), cA, voffA); PG8_STAGE(PG8_SA(0, 1), cA + hstep, voffA);
;         if (wr == 1) PG8_BAR;
;         PG8_WAIT_V(2); PG8_BAR;
;         PG8_STAGE(PG8_SB(1, 0), cB + kstep, voffB); PG8_STAGE(PG8_SA(1, 0), cA + kstep, voffA); PG8_STAGE(PG8_SB(1, 1), cB + hstep + kstep, voffB);
;         PG8_WAIT_V(6); PG8_BAR;
;     } else {
;         PG8_STAGE(PG8_SB(0, 0), cB, voffB); PG8_STAGE(PG8_SA(0, 0), cA, voffA); PG8_STAGE(PG8_SB(0, 1), cB + hstep, voffB); PG8_STAGE(PG8_SA(0, 1), cA + hstep, voffA);
;         if (wr == 1) PG8_BAR;
;         PG8_WAIT_V(4); PG8_BAR;
;         PG8_STAGE(PG8_SB(1, 0), cB + kstep, voffB); PG8_STAGE(PG8_SA(1, 0), cA + kstep, voffA); PG8_STAGE(PG8_SB(1, 1), cB + hstep + kstep, voffB);
;         PG8_WAIT_V(6); PG8_BAR;
.LBB0_980:
	s_or_b64 exec, exec, s[0:1]
	v_readlane_b32 s4, v255, 1
	v_readlane_b32 s5, v255, 2
	s_waitcnt lgkmcnt(0)
	s_barrier
	s_and_b64 vcc, exec, s[4:5]
	v_readfirstlane_b32 s1, v234
	s_cbranch_vccz .LBB0_1000
	v_lshlrev_b32_e32 v0, 4, v234
	v_add_u32_e32 v1, 0x2000, v0
	v_ashrrev_i32_e32 v2, 31, v1
	v_lshrrev_b32_e32 v2, 22, v2
	v_add_u32_e32 v2, v1, v2
	v_ashrrev_i32_e32 v8, 10, v2
	v_mul_i32_i24_e32 v2, 0x400, v8
	v_sub_u32_e32 v1, v1, v2
	v_lshrrev_b32_e32 v2, 4, v1
	v_bitop3_b32 v1, v2, v1, 32 bitop3:0x6c
	v_ashrrev_i32_e32 v2, 31, v1
	v_lshrrev_b32_e32 v2, 26, v2
	v_add_u32_e32 v2, v1, v2
	v_lshlrev_b32_e32 v3, 3, v8
	v_ashrrev_i32_e32 v9, 6, v2
	v_and_b32_e32 v3, -16, v3
	v_add_u32_e32 v3, v9, v3
	v_and_b32_e32 v4, 3, v9
	s_mov_b32 s0, 0x1fffe0
	v_lshrrev_b32_e32 v5, 2, v3
	v_lshlrev_b32_e32 v6, 1, v3
	v_and_b32_e32 v2, 0xc0, v2
	v_and_or_b32 v4, v3, s0, v4
	v_and_b32_e32 v5, 4, v5
	v_and_b32_e32 v6, 24, v6
	v_sub_u32_e32 v1, v1, v2
	v_mov_b32_e32 v2, 1
	v_or3_b32 v4, v4, v5, v6
	v_lshlrev_b32_e32 v5, 5, v8
	v_ashrrev_i16_sdwa v1, v2, sext(v1) dst_sel:DWORD dst_unused:UNUSED_PAD src0_sel:DWORD src1_sel:BYTE_0
	v_and_b32_e32 v5, 32, v5
	v_bfe_i32 v10, v1, 0, 16
	v_add_lshl_u32 v1, v5, v10, 1
	v_lshl_add_u32 v128, v4, 11, v1
	v_lshl_add_u32 v130, v3, 11, v1
	v_bfe_i32 v1, v234, 27, 1
	v_lshrrev_b32_e32 v1, 22, v1
	v_add_u32_e32 v1, v0, v1
	v_and_b32_e32 v1, 0xfffffc00, v1
	v_sub_u32_e32 v0, v0, v1
	v_lshrrev_b32_e32 v1, 4, v0
	v_ashrrev_i32_e32 v3, 31, v234
	v_bitop3_b32 v0, v1, v0, 32 bitop3:0x6c
	v_lshrrev_b32_e32 v3, 26, v3
	v_ashrrev_i32_e32 v1, 31, v0
	v_add_u32_e32 v3, v234, v3
	v_lshrrev_b32_e32 v1, 26, v1
	v_ashrrev_i32_e32 v12, 6, v3
	v_add_u32_e32 v1, v0, v1
	v_lshlrev_b32_e32 v3, 3, v12
	v_ashrrev_i32_e32 v11, 6, v1
	v_and_b32_e32 v3, -16, v3
	v_add_u32_e32 v3, v11, v3
	v_and_b32_e32 v4, 3, v11
	v_and_or_b32 v4, v3, s0, v4
	s_lshr_b32 s0, s93, 29
	s_add_i32 s0, s3, s0
	s_ashr_i32 s4, s0, 3
	s_and_b32 s0, s0, -8
	s_ashr_i32 s6, s1, 6
	s_sub_i32 s0, s3, s0
	s_ashr_i32 s8, s1, 8
	s_lshl_b32 s2, s6, 10
	s_lshl_b32 s7, s0, 6
	s_mul_i32 s5, s0, 0x41
	s_cmp_lt_i32 s0, 0
	s_cselect_b32 s0, s5, s7
	s_add_i32 s0, s0, s4
	s_ashr_i32 s4, s0, 31
	s_lshr_b32 s4, s4, 27
	s_add_i32 s4, s0, s4
	s_ashr_i32 s5, s4, 5
	s_and_b32 s4, s4, 0xffe0
	s_sub_i32 s4, s0, s4
	s_bfe_i32 s0, s4, 0x80000
	s_bfe_u32 s0, s0, 0x3000c
	s_add_i32 s7, s4, s0
	s_bfe_i32 s0, s7, 0x80000
	s_and_b32 s7, s7, 0xf8
	s_sub_i32 s4, s4, s7
	s_lshl_b32 s5, s5, 3
	s_sext_i32_i16 s0, s0
	s_sext_i32_i8 s4, s4
	v_lshrrev_b32_e32 v5, 2, v3
	v_lshlrev_b32_e32 v6, 1, v3
	v_and_b32_e32 v1, 0xc0, v1
	s_lshr_b32 s0, s0, 3
	s_add_i32 s34, s5, s4
	v_and_b32_e32 v5, 4, v5
	v_and_b32_e32 v6, 24, v6
	v_sub_u32_e32 v0, v0, v1
	s_ashr_i32 s35, s34, 31
	s_bfe_i64 s[10:11], s[0:1], 0x100000
	v_or3_b32 v4, v4, v5, v6
	v_lshlrev_b32_e32 v5, 5, v12
	v_ashrrev_i16_sdwa v0, v2, sext(v0) dst_sel:DWORD dst_unused:UNUSED_PAD src0_sel:DWORD src1_sel:BYTE_0
	s_lshl_b64 s[4:5], s[34:35], 19
	s_lshl_b64 s[10:11], s[10:11], 19
	v_and_b32_e32 v5, 32, v5
	v_bfe_i32 v13, v0, 0, 16
	s_add_u32 s38, s28, s10
	v_add_lshl_u32 v0, v5, v13, 1
	s_addc_u32 s39, s29, s11
	s_add_i32 s25, s2, 0
	v_lshl_add_u32 v132, v4, 11, v0
	s_add_i32 m0, s25, 0x10000
	v_lshl_add_u32 v134, v3, 11, v0
	global_load_lds_dwordx4 v132, s[38:39]
	s_add_i32 m0, s25, 0x12000
	s_add_u32 s10, s38, 0x40000
	global_load_lds_dwordx4 v128, s[38:39]
	s_addc_u32 s11, s39, 0
	s_add_i32 m0, s25, 0x14000
	v_mov_b32_e32 v133, 0
	global_load_lds_dwordx4 v132, s[10:11]
	s_add_i32 m0, s25, 0x16000
	s_add_u32 s36, s26, s4
	s_addc_u32 s37, s27, s5
	s_add_i32 s33, s25, 0x2000
	global_load_lds_dwordx4 v128, s[10:11]
	s_mov_b32 m0, s25
	s_add_u32 s4, s36, 0x40000
	global_load_lds_dwordx4 v134, s[36:37]
	s_mov_b32 m0, s33
	s_addc_u32 s5, s37, 0
	s_add_i32 s35, s25, 0x4000
	global_load_lds_dwordx4 v130, s[36:37]
	s_mov_b32 m0, s35
	s_add_i32 s42, s25, 0x6000
	global_load_lds_dwordx4 v134, s[4:5]
	s_mov_b32 m0, s42
	v_mov_b32_e32 v129, v133
	global_load_lds_dwordx4 v130, s[4:5]
	v_mov_b32_e32 v135, v133
	v_mov_b32_e32 v131, v133
	s_cmp_eq_u32 s8, 1
	s_mov_b32 s43, 0
	v_lshl_add_u64 v[6:7], s[38:39], 0, v[132:133]
	v_lshl_add_u64 v[4:5], s[38:39], 0, v[128:129]
	v_lshl_add_u64 v[0:1], s[36:37], 0, v[134:135]
	s_cselect_b64 s[4:5], -1, 0
	v_lshl_add_u64 v[2:3], s[36:37], 0, v[130:131]
	s_and_b32 s9, s6, 3
	s_mov_b64 s[6:7], 0x80
	s_add_i32 m0, s25, 0x18000
	v_lshl_add_u64 v[6:7], v[6:7], 0, s[6:7]
	s_lshl_b32 s12, s8, 13
	s_lshl_b32 s13, s9, 12
	global_load_lds_dwordx4 v[6:7], off
	v_lshl_add_u64 v[4:5], v[4:5], 0, s[6:7]
	s_add_i32 m0, s25, 0x1a000
	s_add_i32 s44, s25, 0x8000
	s_add_i32 s45, s25, 0xa000
	global_load_lds_dwordx4 v[4:5], off
	v_lshl_add_u64 v[0:1], v[0:1], 0, s[6:7]
	s_mov_b32 m0, s44
	s_add_u32 s10, s38, 0x40080
	global_load_lds_dwordx4 v[0:1], off
	v_lshl_add_u64 v[0:1], v[2:3], 0, s[6:7]
	s_mov_b32 m0, s45
	s_addc_u32 s11, s39, 0
	global_load_lds_dwordx4 v[0:1], off
	s_add_i32 m0, s25, 0x1c000
	v_lshl_add_u64 v[0:1], s[10:11], 0, v[132:133]
	global_load_lds_dwordx4 v[0:1], off
	v_lshl_add_u64 v[0:1], s[10:11], 0, v[128:129]
	s_add_i32 m0, s25, 0x1e000
	s_cmpk_lt_u32 s1, 0x100
	global_load_lds_dwordx4 v[0:1], off
	s_cmp_lg_u32 s8, 1
	s_cbranch_scc1 .LBB0_983
	s_barrier
.LBB0_983:
	s_waitcnt vmcnt(8)
	s_barrier
	v_bfe_u32 v1, v234, 4, 2
	v_and_b32_e32 v0, 15, v234
	v_lshlrev_b32_e32 v2, 3, v1
	v_lshlrev_b32_e32 v1, 4, v1
	v_lshl_or_b32 v146, s8, 6, v0
	v_lshl_or_b32 v0, v0, 6, v1
	v_lshlrev_b32_e32 v1, 2, v234
	v_and_b32_e32 v1, 32, v1
	v_bitop3_b32 v3, v0, s12, v1 bitop3:0xde
	v_bitop3_b32 v147, v0, s13, v1 bitop3:0xde
	v_lshlrev_b32_e32 v0, 14, v12
	v_and_b32_e32 v0, 0xffff8000, v0
	v_lshl_add_u32 v0, v11, 11, v0
	v_and_b32_e32 v1, 1, v12
	v_lshl_or_b32 v0, v1, 6, v0
	v_lshl_add_u32 v136, v13, 1, v0
	v_lshlrev_b32_e32 v0, 14, v8
	v_and_b32_e32 v0, 0xffff8000, v0
	s_waitcnt vmcnt(6)
	v_lshl_add_u32 v0, v9, 11, v0
	v_and_b32_e32 v1, 1, v8
	v_lshl_or_b32 v148, s9, 5, v2
	s_cselect_b64 s[8:9], -1, 0
	v_lshl_or_b32 v0, v1, 6, v0
	s_add_i32 s46, 0, 0x10000
	s_add_i32 s47, 0, 0x14000
	s_sext_i32_i8 s50, s0
	v_mov_b32_e32 v137, v133
	v_lshl_add_u32 v138, v10, 1, v0
	v_mov_b32_e32 v139, v133
	v_mov_b64_e32 v[140:141], 0x200
	v_mov_b64_e32 v[142:143], 0x1ff
	v_add_u32_e32 v149, s46, v147
	v_add_u32_e32 v150, s47, v147
	v_add_u32_e32 v151, 0, v3
	s_mov_b64 s[10:11], 0x80000
	s_mov_b64 s[12:13], 0x90000
	s_mov_b64 s[14:15], 0xa0000
	s_mov_b64 s[16:17], 0xb0000
	s_barrier
	s_branch .LBB0_986
